# attention loops: loop-carried SALU/VALU update block moved in front of the loop-back barrier (back-edge rotation), uniform-mask ballot replaced by s_not
# baseline (speedup 1.0000x reference)
.LBB0_512:
	s_mov_b32 s53, s73
	s_mov_b32 s5, s72
	v_add_u32_e32 v50, s56, v243
	ds_read_b64_tr_b16 v[202:203], v50 offset:24576
	ds_read_b64_tr_b16 v[204:205], v50 offset:25088
	v_add_f32_e32 v51, v80, v81
	v_add_f32_e32 v51, v82, v51
	v_add_f32_e32 v51, v83, v51
	v_add_f32_e32 v51, v84, v51
	v_add_f32_e32 v51, v85, v51
	v_cvt_pk_bf16_f32 v198, v80, v81
	v_cvt_pk_bf16_f32 v199, v82, v83
	s_waitcnt lgkmcnt(9)
	v_mfma_f32_32x32x16_bf16 v[96:111], v[114:117], v[140:143], v[32:47]
	ds_read_b64_tr_b16 v[206:207], v50 offset:28672
	ds_read_b64_tr_b16 v[208:209], v50 offset:29184
	s_waitcnt lgkmcnt(10)
	v_mfma_f32_32x32x16_bf16 v[112:127], v[184:187], v[140:143], v[32:47]
	v_add_f32_e32 v51, v86, v51
	v_add_f32_e32 v51, v87, v51
	v_add_f32_e32 v51, v88, v51
	v_add_f32_e32 v51, v89, v51
	v_cvt_pk_bf16_f32 v200, v84, v85
	v_cvt_pk_bf16_f32 v201, v86, v87
	ds_read_b64_tr_b16 v[210:211], v50 offset:25600
	ds_read_b64_tr_b16 v[212:213], v50 offset:26112
	v_add_f32_e32 v51, v90, v51
	v_add_f32_e32 v51, v91, v51
	v_add_f32_e32 v51, v92, v51
	v_add_f32_e32 v51, v93, v51
	v_cvt_pk_bf16_f32 v194, v88, v89
	v_cvt_pk_bf16_f32 v195, v90, v91
	s_waitcnt lgkmcnt(11)
	v_mfma_f32_32x32x16_bf16 v[96:111], v[180:183], v[136:139], v[96:111]
	ds_read_b64_tr_b16 v[180:181], v50 offset:29696
	ds_read_b64_tr_b16 v[182:183], v50 offset:30208
	s_waitcnt lgkmcnt(12)
	v_mfma_f32_32x32x16_bf16 v[112:127], v[176:179], v[136:139], v[112:127]
	v_add_f32_e32 v51, v94, v51
	v_add_f32_e32 v51, v95, v51
	v_add_f32_e32 v51, v64, v51
	v_add_f32_e32 v51, v65, v51
	v_cvt_pk_bf16_f32 v196, v92, v93
	v_cvt_pk_bf16_f32 v197, v94, v95
	ds_read_b64_tr_b16 v[176:177], v50 offset:26624
	ds_read_b64_tr_b16 v[178:179], v50 offset:27136
	v_add_f32_e32 v51, v66, v51
	v_add_f32_e32 v51, v67, v51
	v_add_f32_e32 v51, v68, v51
	v_add_f32_e32 v51, v69, v51
	v_cvt_pk_bf16_f32 v190, v64, v65
	v_cvt_pk_bf16_f32 v191, v66, v67
	s_waitcnt lgkmcnt(13)
	v_mfma_f32_32x32x16_bf16 v[96:111], v[172:175], v[132:135], v[96:111]
	ds_read_b64_tr_b16 v[172:173], v50 offset:30720
	ds_read_b64_tr_b16 v[174:175], v50 offset:31232
	s_waitcnt lgkmcnt(14)
	v_mfma_f32_32x32x16_bf16 v[112:127], v[164:167], v[132:135], v[112:127]
	v_add_f32_e32 v51, v70, v51
	v_add_f32_e32 v51, v71, v51
	v_add_f32_e32 v51, v72, v51
	v_add_f32_e32 v51, v73, v51
	v_cvt_pk_bf16_f32 v192, v68, v69
	v_cvt_pk_bf16_f32 v193, v70, v71
	ds_read_b64_tr_b16 v[164:165], v50 offset:27648
	ds_read_b64_tr_b16 v[166:167], v50 offset:28160
	v_add_f32_e32 v51, v74, v51
	v_add_f32_e32 v51, v75, v51
	v_add_f32_e32 v51, v76, v51
	v_add_f32_e32 v51, v77, v51
	v_cvt_pk_bf16_f32 v186, v72, v73
	v_cvt_pk_bf16_f32 v187, v74, v75
	s_waitcnt lgkmcnt(14)
	v_mfma_f32_32x32x16_bf16 v[96:111], v[168:171], v[128:131], v[96:111]
	ds_read_b64_tr_b16 v[168:169], v50 offset:31744
	ds_read_b64_tr_b16 v[170:171], v50 offset:32256
	v_mfma_f32_32x32x16_bf16 v[112:127], v[160:163], v[128:131], v[112:127]
	v_add_f32_e32 v50, v78, v51
	v_add_f32_e32 v50, v79, v50
	v_add_f32_e32 v184, 0, v50
	v_cvt_pk_bf16_f32 v188, v76, v77
	v_cvt_pk_bf16_f32 v189, v78, v79
	v_lshl_add_u64 v[50:51], v[230:231], 0, s[38:39]
	s_add_i32 s26, s72, s69
	s_mov_b32 s27, m0
	s_mov_b32 m0, s26
	s_nop 0
	global_load_lds_dwordx4 v[50:51], off
	s_mov_b32 m0, s27
	v_lshl_add_u64 v[50:51], v[228:229], 0, s[38:39]
	s_add_i32 s26, s73, s70
	s_mov_b32 s27, m0
	s_mov_b32 m0, s26
	s_nop 0
	global_load_lds_dwordx4 v[50:51], off
	s_mov_b32 m0, s27
	ds_read_b128 v[50:53], v49
	ds_read_b128 v[54:57], v49 offset:128
	ds_read_b128 v[58:61], v49 offset:32
	s_waitcnt lgkmcnt(2)
	v_add_f32_e32 v82, v96, v50
	v_add_f32_e32 v83, v97, v51
	v_add_f32_e32 v84, v98, v52
	v_add_f32_e32 v85, v99, v53
	ds_read_b128 v[50:53], v49 offset:160
	s_waitcnt lgkmcnt(2)
	v_add_f32_e32 v86, v112, v54
	v_add_f32_e32 v87, v113, v55
	v_add_f32_e32 v88, v114, v56
	v_add_f32_e32 v89, v115, v57
	s_waitcnt lgkmcnt(1)
	v_pk_add_f32 v[70:71], v[100:101], v[58:59]
	v_pk_add_f32 v[72:73], v[102:103], v[60:61]
	ds_read_b128 v[58:61], v49 offset:64
	s_waitcnt lgkmcnt(1)
	v_pk_add_f32 v[54:55], v[116:117], v[50:51]
	v_pk_add_f32 v[56:57], v[118:119], v[52:53]
	ds_read_b128 v[50:53], v49 offset:192
	ds_read_b128 v[62:65], v49 offset:96
	ds_read_b128 v[66:69], v49 offset:224
	s_waitcnt lgkmcnt(3)
	v_pk_add_f32 v[74:75], v[104:105], v[58:59]
	v_pk_add_f32 v[76:77], v[106:107], v[60:61]
	s_waitcnt lgkmcnt(2)
	v_pk_add_f32 v[58:59], v[120:121], v[50:51]
	s_waitcnt lgkmcnt(1)
	v_pk_add_f32 v[78:79], v[108:109], v[62:63]
	v_pk_add_f32 v[80:81], v[110:111], v[64:65]
	s_waitcnt lgkmcnt(0)
	v_pk_add_f32 v[64:65], v[126:127], v[68:69]
	v_pk_add_f32 v[60:61], v[122:123], v[52:53]
	v_pk_add_f32 v[62:63], v[124:125], v[66:67]
	v_exp_f32_e32 v66, v82
	v_exp_f32_e32 v67, v83
	v_exp_f32_e32 v68, v84
	v_exp_f32_e32 v69, v85
	s_nop 0
	v_exp_f32_e32 v70, v70
	v_exp_f32_e32 v71, v71
	v_exp_f32_e32 v72, v72
	v_exp_f32_e32 v73, v73
	v_add_u32_e32 v82, s53, v241
	ds_read_b128 v[98:101], v82
	ds_read_b128 v[118:121], v82 offset:512
	v_exp_f32_e32 v74, v74
	v_exp_f32_e32 v75, v75
	v_exp_f32_e32 v76, v76
	v_exp_f32_e32 v77, v77
	ds_read_b128 v[122:125], v82 offset:2048
	ds_read_b128 v[144:147], v82 offset:2560
	v_exp_f32_e32 v78, v78
	v_exp_f32_e32 v79, v79
	v_exp_f32_e32 v80, v80
	v_exp_f32_e32 v81, v81
	ds_read_b128 v[148:151], v82 offset:4096
	ds_read_b128 v[244:247], v82 offset:4608
	v_exp_f32_e32 v50, v86
	v_exp_f32_e32 v51, v87
	v_exp_f32_e32 v52, v88
	v_exp_f32_e32 v53, v89
	ds_read_b128 v[248:251], v82 offset:6144
	ds_read_b128 v[234:237], v82 offset:6656
	v_exp_f32_e32 v54, v54
	v_exp_f32_e32 v55, v55
	v_exp_f32_e32 v56, v56
	v_exp_f32_e32 v57, v57
	s_nop 0
	v_exp_f32_e32 v58, v58
	v_exp_f32_e32 v59, v59
	v_exp_f32_e32 v60, v60
	v_exp_f32_e32 v61, v61
	s_nop 0
	v_exp_f32_e32 v62, v62
	v_exp_f32_e32 v63, v63
	v_exp_f32_e32 v64, v64
	v_exp_f32_e32 v65, v65
	s_waitcnt vmcnt(2) lgkmcnt(0)
	s_barrier
	s_add_i32 s26, s73, 0x2000
	s_cmpk_lg_i32 s73, 0x4000
	s_cselect_b32 s72, s26, 0
	v_add_u32_e32 v126, s5, v243
	ds_read_b64_tr_b16 v[218:219], v126 offset:24576
	ds_read_b64_tr_b16 v[220:221], v126 offset:25088
	v_add_f32_e32 v82, v66, v67
	v_add_f32_e32 v82, v68, v82
	v_add_f32_e32 v82, v69, v82
	v_add_f32_e32 v82, v70, v82
	v_add_f32_e32 v102, v71, v82
	s_waitcnt lgkmcnt(9)
	v_mfma_f32_32x32x16_bf16 v[82:97], v[98:101], v[140:143], v[32:47]
	v_cvt_pk_bf16_f32 v66, v66, v67
	v_mov_b64_e32 v[156:157], v[198:199]
	v_mov_b64_e32 v[158:159], v[200:201]
	v_mov_b32_e32 v156, v66
	v_cvt_pk_bf16_f32 v157, v68, v69
	ds_read_b64_tr_b16 v[114:115], v126 offset:28672
	ds_read_b64_tr_b16 v[116:117], v126 offset:29184
	v_add_f32_e32 v66, v72, v102
	v_add_f32_e32 v66, v73, v66
	v_add_f32_e32 v66, v74, v66
	v_add_f32_e32 v66, v75, v66
	v_cvt_pk_bf16_f32 v158, v70, v71
	v_cvt_pk_bf16_f32 v159, v72, v73
	s_waitcnt lgkmcnt(10)
	v_mfma_f32_32x32x16_bf16 v[98:113], v[118:121], v[140:143], v[32:47]
	ds_read_b64_tr_b16 v[214:215], v126 offset:25600
	ds_read_b64_tr_b16 v[216:217], v126 offset:26112
	s_waitcnt lgkmcnt(11)
	v_mfma_f32_32x32x16_bf16 v[82:97], v[122:125], v[136:139], v[82:97]
	v_add_f32_e32 v66, v76, v66
	v_add_f32_e32 v66, v77, v66
	v_add_f32_e32 v66, v78, v66
	v_cvt_pk_bf16_f32 v67, v74, v75
	v_mov_b64_e32 v[152:153], v[194:195]
	v_add_f32_e32 v66, v79, v66
	v_mov_b64_e32 v[154:155], v[196:197]
	v_mov_b32_e32 v152, v67
	v_cvt_pk_bf16_f32 v153, v76, v77
	ds_read_b64_tr_b16 v[160:161], v126 offset:29696
	ds_read_b64_tr_b16 v[162:163], v126 offset:30208
	v_add_f32_e32 v66, v80, v66
	v_add_f32_e32 v66, v81, v66
	v_add_f32_e32 v66, v50, v66
	v_add_f32_e32 v66, v51, v66
	v_cvt_pk_bf16_f32 v154, v78, v79
	v_cvt_pk_bf16_f32 v155, v80, v81
	s_waitcnt lgkmcnt(12)
	v_mfma_f32_32x32x16_bf16 v[98:113], v[144:147], v[136:139], v[98:113]
	ds_read_b64_tr_b16 v[122:123], v126 offset:26624
	ds_read_b64_tr_b16 v[124:125], v126 offset:27136
	s_waitcnt lgkmcnt(13)
	v_mfma_f32_32x32x16_bf16 v[82:97], v[148:151], v[132:135], v[82:97]
	v_add_f32_e32 v66, v52, v66
	v_add_f32_e32 v66, v53, v66
	v_add_f32_e32 v66, v54, v66
	v_cvt_pk_bf16_f32 v50, v50, v51
	v_mov_b64_e32 v[148:149], v[190:191]
	v_add_f32_e32 v66, v55, v66
	v_mov_b64_e32 v[150:151], v[192:193]
	v_mov_b32_e32 v148, v50
	v_cvt_pk_bf16_f32 v149, v52, v53
	ds_read_b64_tr_b16 v[118:119], v126 offset:30720
	ds_read_b64_tr_b16 v[120:121], v126 offset:31232
	v_add_f32_e32 v50, v56, v66
	v_add_f32_e32 v50, v57, v50
	v_add_f32_e32 v50, v58, v50
	v_add_f32_e32 v50, v59, v50
	v_cvt_pk_bf16_f32 v150, v54, v55
	v_cvt_pk_bf16_f32 v151, v56, v57
	s_waitcnt lgkmcnt(14)
	v_mfma_f32_32x32x16_bf16 v[98:113], v[244:247], v[132:135], v[98:113]
	ds_read_b64_tr_b16 v[54:55], v126 offset:27648
	ds_read_b64_tr_b16 v[56:57], v126 offset:28160
	s_waitcnt lgkmcnt(14)
	v_mfma_f32_32x32x16_bf16 v[82:97], v[248:251], v[128:131], v[82:97]
	v_add_f32_e32 v50, v60, v50
	v_add_f32_e32 v50, v61, v50
	v_add_f32_e32 v50, v62, v50
	v_add_f32_e32 v66, v63, v50
	v_cvt_pk_bf16_f32 v50, v58, v59
	v_mov_b64_e32 v[144:145], v[186:187]
	v_mov_b64_e32 v[146:147], v[188:189]
	v_mov_b32_e32 v144, v50
	v_cvt_pk_bf16_f32 v145, v60, v61
	ds_read_b64_tr_b16 v[50:51], v126 offset:31744
	ds_read_b64_tr_b16 v[52:53], v126 offset:32256
	v_add_f32_e32 v58, v64, v66
	v_add_f32_e32 v58, v65, v58
	v_add_f32_e32 v58, 0, v58
	v_cvt_pk_bf16_f32 v146, v62, v63
	v_cvt_pk_bf16_f32 v147, v64, v65
	v_mfma_f32_32x32x16_bf16 v[98:113], v[234:237], v[128:131], v[98:113]
	v_mfma_f32_32x32x16_bf16 v[0:15], v[198:201], v[202:205], v[0:15]
	s_add_i32 s5, s73, s69
	s_mov_b32 s27, m0
	s_mov_b32 m0, s5
	s_nop 0
	global_load_lds_dwordx4 v[230:231], off
	s_mov_b32 m0, s27
	s_add_i32 s26, s72, s70
	v_add_f32_e32 v48, v48, v184
	s_mov_b32 s5, m0
	s_mov_b32 m0, s26
	s_nop 0
	global_load_lds_dwordx4 v[228:229], off
	s_mov_b32 m0, s5
	v_add_f32_e32 v48, v48, v58
	s_add_i32 s0, s0, 2
	v_mfma_f32_32x32x16_bf16 v[16:31], v[198:201], v[206:209], v[16:31]
	v_mfma_f32_32x32x16_bf16 v[0:15], v[194:197], v[210:213], v[0:15]
	v_mfma_f32_32x32x16_bf16 v[16:31], v[194:197], v[180:183], v[16:31]
	v_mfma_f32_32x32x16_bf16 v[0:15], v[190:193], v[176:179], v[0:15]
	ds_read_b128 v[58:61], v49 offset:256
	ds_read_b128 v[62:65], v49 offset:288
	ds_read_b128 v[66:69], v49 offset:384
	ds_read_b128 v[70:73], v49 offset:416
	ds_read_b128 v[74:77], v49 offset:448
	ds_read_b128 v[78:81], v49 offset:320
	ds_read_b128 v[176:179], v49 offset:352
	s_waitcnt lgkmcnt(6)
	v_add_f32_e32 v60, v84, v60
	v_add_f32_e32 v61, v85, v61
	s_waitcnt lgkmcnt(4)
	v_add_f32_e32 v66, v98, v66
	v_add_f32_e32 v67, v99, v67
	v_add_f32_e32 v98, v100, v68
	v_add_f32_e32 v99, v101, v69
	v_mfma_f32_32x32x16_bf16 v[16:31], v[190:193], v[172:175], v[16:31]
	ds_read_b128 v[172:175], v49 offset:480
	v_add_f32_e64 v84, v86, v62
	v_add_f32_e64 v85, v87, v63
	v_add_f32_e64 v86, v88, v64
	v_add_f32_e64 v87, v89, v65
	s_waitcnt lgkmcnt(4)
	v_pk_add_f32 v[68:69], v[102:103], v[70:71]
	v_pk_add_f32 v[70:71], v[104:105], v[72:73]
	s_waitcnt lgkmcnt(2)
	v_pk_add_f32 v[88:89], v[90:91], v[78:79]
	v_pk_add_f32 v[90:91], v[92:93], v[80:81]
	v_mfma_f32_32x32x16_bf16 v[0:15], v[186:189], v[164:167], v[0:15]
	v_add_f32_e64 v72, v106, v74
	v_add_f32_e64 v73, v107, v75
	v_add_f32_e64 v74, v108, v76
	v_add_f32_e64 v75, v109, v77
	s_waitcnt lgkmcnt(1)
	v_pk_add_f32 v[92:93], v[94:95], v[176:177]
	v_pk_add_f32 v[94:95], v[96:97], v[178:179]
	s_waitcnt lgkmcnt(0)
	v_pk_add_f32 v[76:77], v[110:111], v[172:173]
	v_pk_add_f32 v[78:79], v[112:113], v[174:175]
	v_add_f32_e32 v58, v82, v58
	v_mfma_f32_32x32x16_bf16 v[16:31], v[186:189], v[168:171], v[16:31]
	v_add_f32_e32 v59, v83, v59
	v_mfma_f32_32x32x16_bf16 v[0:15], v[156:159], v[218:221], v[0:15]
	v_exp_f32_e32 v80, v58
	v_exp_f32_e32 v81, v59
	v_exp_f32_e32 v82, v60
	v_exp_f32_e32 v83, v61
	v_mfma_f32_32x32x16_bf16 v[16:31], v[156:159], v[114:117], v[16:31]
	v_exp_f32_e32 v84, v84
	v_exp_f32_e32 v85, v85
	v_exp_f32_e32 v86, v86
	v_exp_f32_e32 v87, v87
	v_add_u32_e32 v58, s72, v241
	ds_read_b128 v[114:117], v58
	ds_read_b128 v[184:187], v58 offset:512
	v_mfma_f32_32x32x16_bf16 v[0:15], v[152:155], v[214:217], v[0:15]
	v_exp_f32_e32 v88, v88
	v_exp_f32_e32 v89, v89
	v_exp_f32_e32 v90, v90
	v_exp_f32_e32 v91, v91
	ds_read_b128 v[180:183], v58 offset:2048
	ds_read_b128 v[176:179], v58 offset:2560
	v_mfma_f32_32x32x16_bf16 v[16:31], v[152:155], v[160:163], v[16:31]
	v_exp_f32_e32 v92, v92
	v_exp_f32_e32 v93, v93
	v_exp_f32_e32 v94, v94
	v_exp_f32_e32 v95, v95
	ds_read_b128 v[172:175], v58 offset:4096
	ds_read_b128 v[164:167], v58 offset:4608
	v_mfma_f32_32x32x16_bf16 v[0:15], v[148:151], v[122:125], v[0:15]
	v_exp_f32_e32 v64, v66
	v_exp_f32_e32 v65, v67
	v_exp_f32_e32 v66, v98
	v_exp_f32_e32 v67, v99
	ds_read_b128 v[168:171], v58 offset:6144
	ds_read_b128 v[160:163], v58 offset:6656
	v_mfma_f32_32x32x16_bf16 v[16:31], v[148:151], v[118:121], v[16:31]
	v_exp_f32_e32 v68, v68
	v_exp_f32_e32 v69, v69
	v_exp_f32_e32 v70, v70
	v_exp_f32_e32 v71, v71
	v_mfma_f32_32x32x16_bf16 v[0:15], v[144:147], v[54:57], v[0:15]
	v_exp_f32_e32 v72, v72
	v_exp_f32_e32 v73, v73
	v_exp_f32_e32 v74, v74
	v_exp_f32_e32 v75, v75
	v_mfma_f32_32x32x16_bf16 v[16:31], v[144:147], v[50:53], v[16:31]
	v_exp_f32_e32 v76, v76
	v_exp_f32_e32 v77, v77
	v_exp_f32_e32 v78, v78
	v_exp_f32_e32 v79, v79
	s_waitcnt vmcnt(2) lgkmcnt(0)
	s_add_i32 s5, s72, 0x2000
	s_cmpk_lg_i32 s72, 0x4000
	s_cselect_b32 s73, s5, 0
	v_lshl_add_u64 v[228:229], v[228:229], 0, s[22:23]
	v_lshl_add_u64 v[230:231], v[230:231], 0, s[22:23]
	v_add_u32_e32 v49, 0x200, v49
	s_cmp_ge_i32 s0, s4
	s_mov_b32 s56, s53
	v_mov_b32_e32 v200, v158
	v_mov_b32_e32 v201, v159
	v_mov_b32_e32 v196, v154
	v_mov_b32_e32 v197, v155
	v_mov_b32_e32 v192, v150
	v_mov_b32_e32 v193, v151
	v_mov_b32_e32 v188, v146
	v_mov_b32_e32 v189, v147
	s_barrier
	s_cbranch_scc0 .LBB0_512
	s_add_i32 s4, s0, 1
	s_cmp_ge_u32 s4, s71
	s_cbranch_scc1 .LBB0_552

.LBB0_533:
	ds_read_b128 v[66:69], v49 offset:256
	ds_read_b128 v[76:79], v49 offset:288
	s_waitcnt lgkmcnt(1)
	v_add_f32_e32 v100, v100, v68
	v_add_f32_e32 v101, v101, v69
	ds_read_b128 v[72:75], v49 offset:384
	ds_read_b128 v[68:71], v49 offset:416
	ds_read_b128 v[80:83], v49 offset:320
	v_add_f32_e32 v66, v98, v66
	v_add_f32_e32 v67, v99, v67
	s_waitcnt lgkmcnt(3)
	v_pk_add_f32 v[84:85], v[102:103], v[76:77]
	v_pk_add_f32 v[86:87], v[104:105], v[78:79]
	ds_read_b128 v[92:95], v49 offset:352
	ds_read_b128 v[96:99], v49 offset:448
	ds_read_b128 v[76:79], v49 offset:480
	s_waitcnt lgkmcnt(3)
	v_pk_add_f32 v[88:89], v[106:107], v[80:81]
	v_pk_add_f32 v[90:91], v[108:109], v[82:83]
	s_waitcnt lgkmcnt(2)
	v_pk_add_f32 v[92:93], v[110:111], v[92:93]
	v_pk_add_f32 v[94:95], v[112:113], v[94:95]
	v_mfma_f32_32x32x16_bf16 v[0:15], v[156:159], v[208:211], v[0:15]
	v_exp_f32_e32 v80, v66
	v_exp_f32_e32 v81, v67
	v_exp_f32_e32 v82, v100
	v_exp_f32_e32 v83, v101
	v_mfma_f32_32x32x16_bf16 v[16:31], v[156:159], v[204:207], v[16:31]
	v_exp_f32_e32 v84, v84
	v_exp_f32_e32 v85, v85
	v_exp_f32_e32 v86, v86
	v_exp_f32_e32 v87, v87
	s_not_b64 s[4:5], s[58:59]
	s_andn2_b64 vcc, exec, s[58:59]
	v_add_u32_e32 v100, s72, v241
	s_cbranch_vccnz .LBB0_535
	ds_read_b128 v[114:117], v100
	ds_read_b128 v[184:187], v100 offset:512

.LBB0_541:
	v_mfma_f32_32x32x16_bf16 v[16:31], v[148:151], v[188:191], v[16:31]
	v_exp_f32_e32 v68, v68
	v_exp_f32_e32 v69, v69
	v_exp_f32_e32 v70, v70
	v_exp_f32_e32 v71, v71
	v_mfma_f32_32x32x16_bf16 v[0:15], v[144:147], v[122:125], v[0:15]
	v_exp_f32_e32 v72, v72
	v_exp_f32_e32 v73, v73
	v_exp_f32_e32 v74, v74
	v_exp_f32_e32 v75, v75
	v_mfma_f32_32x32x16_bf16 v[16:31], v[144:147], v[118:121], v[16:31]
	v_exp_f32_e32 v76, v76
	v_exp_f32_e32 v77, v77
	v_exp_f32_e32 v78, v78
	v_exp_f32_e32 v79, v79
	s_add_i32 s0, s72, 0x2000
	s_cmpk_lg_i32 s72, 0x4000
	v_add_f32_e32 v48, v48, v217
	s_cselect_b32 s0, s0, 0
	v_add_f32_e32 v48, v48, v126
	v_add_u32_e32 v49, 0x200, v49
	v_add_u32_e32 v216, 0x80, v216
	v_lshl_add_u64 v[212:213], v[212:213], 0, s[22:23]
	v_lshl_add_u64 v[214:215], v[214:215], 0, s[22:23]
	s_mov_b64 s[4:5], -1
	s_and_b64 vcc, exec, s[56:57]
	s_cbranch_vccz .LBB0_547
	s_and_b64 vcc, exec, s[52:53]
	s_cbranch_vccz .LBB0_544
	s_waitcnt vmcnt(0) lgkmcnt(0)
	s_barrier
	s_mov_b64 s[4:5], 0

.LBB0_549:
	s_add_i32 s4, s77, -1
	s_cmp_lt_u32 s4, s71
	s_cbranch_scc0 .LBB0_553
	s_mov_b32 s76, s77
	s_mov_b32 s53, s73
	s_mov_b32 s73, s0
	s_branch .LBB0_515
